# GEMM1 V-tile epilogue: V^T 2-byte stores use one base address + immediate offsets, paired bf16 converts (short + short_d16_hi)
# baseline (speedup 1.0000x reference)
.LBB0_210:
	v_ashrrev_i32_e32 v98, 6, v118
	v_and_b32_e32 v100, 1, v98
	v_cmp_eq_u32_e32 vcc, 1, v100
	s_movk_i32 s3, 0x2200
	v_mul_lo_u32 v101, v98, s3
	v_cndmask_b32_e32 v100, 0, v125, vcc
	v_add_u32_e32 v108, s6, v100
	v_ashrrev_i32_e32 v100, 1, v118
	v_and_b32_e32 v100, 0xffffffc0, v100
	v_add_u32_e32 v116, s4, v100
	s_movk_i32 s3, 0x3ff
	v_cmp_lt_i32_e64 s[10:11], s3, v116
	v_add_u32_e32 v98, 0xfffff400, v116
	s_movk_i32 s3, 0xf9ff
	v_cmp_lt_u32_e64 s[8:9], s3, v98
	v_subrev_co_u32_e32 v98, vcc, 0xa00, v116
	v_lshrrev_b32_e32 v100, 6, v98
	s_movk_i32 s3, 0x180
	v_mad_u64_u32 v[112:113], s[4:5], v100, s3, 0
	s_movk_i32 s3, 0x800
	v_lshrrev_b32_e32 v100, 3, v118
	v_lshlrev_b32_e32 v102, 2, v118
	v_cmp_gt_u32_e64 s[6:7], s3, v116
	s_movk_i32 s3, 0x7ff
	v_and_b32_e32 v159, 4, v100
	v_and_b32_e32 v100, 32, v118
	v_and_b32_e32 v155, 60, v102
	v_cmp_lt_u32_e64 s[4:5], s3, v116
	v_lshl_or_b32 v158, v100, 2, v101
	v_lshl_or_b32 v139, v155, 2, v101
	v_cndmask_b32_e64 v101, v128, v129, s[4:5]
	v_add_u32_e32 v102, v101, v116
	v_bfe_u32 v154, v118, 4, 2
	v_lshrrev_b32_e32 v105, 6, v102
	s_movk_i32 s3, 0x6000
	v_and_b32_e32 v161, 31, v118
	v_or_b32_e32 v151, 4, v154
	v_or_b32_e32 v148, 8, v154
	v_or_b32_e32 v146, 12, v154
	v_or_b32_e32 v144, 16, v154
	v_or_b32_e32 v142, 20, v154
	v_or_b32_e32 v138, 24, v154
	v_or_b32_e32 v136, 28, v154
	v_ashrrev_i32_e32 v103, 31, v102
	v_mul_lo_u32 v106, v105, s3
	s_movk_i32 s3, 0x600
	v_mov_b32_e32 v117, v99
	s_xor_b64 s[30:31], vcc, -1
	v_mul_u32_u24_e32 v157, 0x110, v161
	v_mad_u32_u24 v156, v161, s56, v158
	v_lshlrev_b32_e32 v153, 9, v154
	v_mul_u32_u24_e32 v152, 0x110, v154
	v_lshlrev_b32_e32 v150, 9, v151
	v_mad_u32_u24 v149, v154, s56, v126
	v_lshlrev_b32_e32 v147, 9, v148
	v_mad_u32_u24 v141, v154, s56, v127
	v_lshlrev_b32_e32 v145, 9, v146
	v_lshlrev_b32_e32 v143, 9, v144
	v_lshlrev_b32_e32 v140, 9, v142
	v_lshlrev_b32_e32 v137, 9, v138
	v_lshlrev_b32_e32 v135, 9, v136
	v_cndmask_b32_e64 v104, v130, 1.0, s[4:5]
	v_mov_b32_e32 v101, v99
	v_ashrrev_i32_e32 v107, 31, v106
	v_cmp_gt_u32_e32 vcc, s3, v116
	v_lshl_add_u64 v[110:111], v[102:103], 1, s[20:21]
	v_lshl_add_u64 v[114:115], v[116:117], 1, s[96:97]
	v_or_b32_e32 v118, v108, v161
	s_and_saveexec_b64 s[12:13], s[10:11]
	s_xor_b64 s[34:35], exec, s[12:13]
	s_cbranch_execz .LBB0_266
	s_and_saveexec_b64 s[12:13], s[8:9]
	s_xor_b64 s[36:37], exec, s[12:13]
	s_cbranch_execz .LBB0_263
	v_cmp_gt_i32_e64 s[12:13], s57, v108
	s_and_saveexec_b64 s[14:15], s[30:31]
	s_xor_b64 s[38:39], exec, s[14:15]
	s_cbranch_execz .LBB0_231
	v_ashrrev_i32_e32 v120, 6, v108
	v_ashrrev_i32_e32 v121, 31, v120
	v_lshl_add_u64 v[120:121], v[112:113], 0, v[120:121]
	v_lshlrev_b64 v[120:121], 6, v[120:121]
	v_and_b32_e32 v105, 63, v118
	v_lshlrev_b32_e32 v118, 1, v105
	v_mov_b32_e32 v119, v99
	v_or3_b32 v122, v120, v159, 32
	v_mov_b32_e32 v123, v121
	v_lshl_add_u64 v[118:119], s[24:25], 0, v[118:119]
	v_lshlrev_b64 v[122:123], 7, v[122:123]
	v_cvt_pk_bf16_f32 v105, v82, v83
	v_lshl_add_u64 v[122:123], v[118:119], 0, v[122:123]
	v_cvt_pk_bf16_f32 v109, v84, v85
	global_store_short v[122:123], v105, off offset:-4096
	global_store_short_d16_hi v[122:123], v105, off offset:-3968
	v_cvt_pk_bf16_f32 v117, v86, v87
	global_store_short v[122:123], v109, off offset:-3840
	global_store_short_d16_hi v[122:123], v109, off offset:-3712
	v_cvt_pk_bf16_f32 v162, v88, v89
	global_store_short v[122:123], v117, off offset:-3072
	global_store_short_d16_hi v[122:123], v117, off offset:-2944
	v_cvt_pk_bf16_f32 v163, v90, v91
	global_store_short v[122:123], v162, off offset:-2816
	global_store_short_d16_hi v[122:123], v162, off offset:-2688
	v_cvt_pk_bf16_f32 v164, v92, v93
	global_store_short v[122:123], v163, off offset:-2048
	global_store_short_d16_hi v[122:123], v163, off offset:-1920
	v_cvt_pk_bf16_f32 v165, v94, v95
	global_store_short v[122:123], v164, off offset:-1792
	global_store_short_d16_hi v[122:123], v164, off offset:-1664
	v_cvt_pk_bf16_f32 v166, v96, v97
	global_store_short v[122:123], v165, off offset:-1024
	global_store_short_d16_hi v[122:123], v165, off offset:-896
	v_cvt_pk_bf16_f32 v167, v66, v67
	global_store_short v[122:123], v166, off offset:-768
	global_store_short_d16_hi v[122:123], v166, off offset:-640
	v_cvt_pk_bf16_f32 v168, v68, v69
	global_store_short v[122:123], v167, off
	global_store_short_d16_hi v[122:123], v167, off offset:128
	v_cvt_pk_bf16_f32 v169, v70, v71
	global_store_short v[122:123], v168, off offset:256
	global_store_short_d16_hi v[122:123], v168, off offset:384
	v_cvt_pk_bf16_f32 v170, v72, v73
	global_store_short v[122:123], v169, off offset:1024
	global_store_short_d16_hi v[122:123], v169, off offset:1152
	v_cvt_pk_bf16_f32 v171, v74, v75
	global_store_short v[122:123], v170, off offset:1280
	global_store_short_d16_hi v[122:123], v170, off offset:1408
	v_cvt_pk_bf16_f32 v172, v76, v77
	global_store_short v[122:123], v171, off offset:2048
	global_store_short_d16_hi v[122:123], v171, off offset:2176
	v_cvt_pk_bf16_f32 v173, v78, v79
	global_store_short v[122:123], v172, off offset:2304
	global_store_short_d16_hi v[122:123], v172, off offset:2432
	v_cvt_pk_bf16_f32 v174, v80, v81
	global_store_short v[122:123], v173, off offset:3072
	global_store_short_d16_hi v[122:123], v173, off offset:3200
	global_store_short v[122:123], v174, off offset:3328
	global_store_short_d16_hi v[122:123], v174, off offset:3456
	s_and_saveexec_b64 s[40:41], s[12:13]
	s_cbranch_execz .LBB0_230
	v_permlane32_swap_b32_e32 v82, v66
	v_permlane32_swap_b32_e32 v83, v67
	v_permlane32_swap_b32_e32 v84, v68
	v_permlane32_swap_b32_e32 v85, v69
	v_ashrrev_i32_e32 v109, 31, v108
	v_permlane32_swap_b32_e32 v86, v70
	v_permlane32_swap_b32_e32 v87, v71
	v_permlane32_swap_b32_e32 v88, v72
	v_permlane32_swap_b32_e32 v89, v73
	v_permlane32_swap_b32_e32 v90, v74
	v_permlane32_swap_b32_e32 v91, v75
	v_permlane32_swap_b32_e32 v92, v76
	v_permlane32_swap_b32_e32 v93, v77
	v_permlane32_swap_b32_e32 v94, v78
	v_permlane32_swap_b32_e32 v95, v79
	v_permlane32_swap_b32_e32 v96, v80
	v_permlane32_swap_b32_e32 v97, v81
	ds_write_b128 v156, v[82:85]
	ds_write_b128 v156, v[66:69] offset:16
	ds_write_b128 v156, v[86:89] offset:32
	ds_write_b128 v156, v[70:73] offset:48
	ds_write_b128 v156, v[90:93] offset:64
	ds_write_b128 v156, v[74:77] offset:80
	ds_write_b128 v156, v[94:97] offset:96
	ds_write_b128 v156, v[78:81] offset:112
	v_lshlrev_b64 v[66:67], 11, v[108:109]
	v_lshl_add_u64 v[66:67], s[26:27], 0, v[66:67]
	v_lshl_add_u64 v[66:67], v[98:99], 2, v[66:67]
	v_lshlrev_b32_e32 v68, 2, v155
	v_mov_b32_e32 v69, v99
	v_lshl_add_u64 v[66:67], v[66:67], 0, v[68:69]
	v_or_b32_e32 v68, v108, v154
	v_cmp_gt_i32_e64 s[14:15], s57, v68
	s_and_saveexec_b64 s[42:43], s[14:15]
	s_cbranch_execz .LBB0_216
	v_lshlrev_b32_e32 v68, 2, v153
	v_mov_b32_e32 v69, v99
	v_lshl_add_u64 v[72:73], v[66:67], 0, v[68:69]
	v_add_u32_e32 v68, v139, v152
	ds_read_b128 v[68:71], v68
	s_waitcnt lgkmcnt(0)
	global_store_dwordx4 v[72:73], v[68:71], off

.LBB0_268:
	s_or_b64 exec, exec, s[14:15]
	s_nop 0
	v_add_u32_e32 v66, 32, v108
	v_or_b32_e32 v68, v66, v161
	s_and_saveexec_b64 s[12:13], s[10:11]
	s_xor_b64 s[34:35], exec, s[12:13]
	s_cbranch_execz .LBB0_324
	s_and_saveexec_b64 s[12:13], s[8:9]
	s_xor_b64 s[36:37], exec, s[12:13]
	s_cbranch_execz .LBB0_321
	v_cmp_gt_i32_e64 s[12:13], s59, v108
	s_and_saveexec_b64 s[14:15], s[30:31]
	s_xor_b64 s[38:39], exec, s[14:15]
	s_cbranch_execz .LBB0_289
	v_ashrrev_i32_e32 v70, 6, v66
	v_ashrrev_i32_e32 v71, 31, v70
	v_lshl_add_u64 v[70:71], v[112:113], 0, v[70:71]
	v_lshlrev_b64 v[70:71], 6, v[70:71]
	v_and_b32_e32 v67, 63, v68
	v_lshlrev_b32_e32 v68, 1, v67
	v_mov_b32_e32 v69, v99
	v_or3_b32 v72, v70, v159, 32
	v_mov_b32_e32 v73, v71
	v_lshl_add_u64 v[68:69], s[24:25], 0, v[68:69]
	v_lshlrev_b64 v[72:73], 7, v[72:73]
	v_cvt_pk_bf16_f32 v67, v50, v51
	v_lshl_add_u64 v[72:73], v[68:69], 0, v[72:73]
	v_cvt_pk_bf16_f32 v74, v52, v53
	global_store_short v[72:73], v67, off offset:-4096
	global_store_short_d16_hi v[72:73], v67, off offset:-3968
	v_cvt_pk_bf16_f32 v75, v54, v55
	global_store_short v[72:73], v74, off offset:-3840
	global_store_short_d16_hi v[72:73], v74, off offset:-3712
	v_cvt_pk_bf16_f32 v76, v56, v57
	global_store_short v[72:73], v75, off offset:-3072
	global_store_short_d16_hi v[72:73], v75, off offset:-2944
	v_cvt_pk_bf16_f32 v77, v58, v59
	global_store_short v[72:73], v76, off offset:-2816
	global_store_short_d16_hi v[72:73], v76, off offset:-2688
	v_cvt_pk_bf16_f32 v78, v60, v61
	global_store_short v[72:73], v77, off offset:-2048
	global_store_short_d16_hi v[72:73], v77, off offset:-1920
	v_cvt_pk_bf16_f32 v79, v62, v63
	global_store_short v[72:73], v78, off offset:-1792
	global_store_short_d16_hi v[72:73], v78, off offset:-1664
	v_cvt_pk_bf16_f32 v80, v64, v65
	global_store_short v[72:73], v79, off offset:-1024
	global_store_short_d16_hi v[72:73], v79, off offset:-896
	v_cvt_pk_bf16_f32 v81, v34, v35
	global_store_short v[72:73], v80, off offset:-768
	global_store_short_d16_hi v[72:73], v80, off offset:-640
	v_cvt_pk_bf16_f32 v82, v36, v37
	global_store_short v[72:73], v81, off
	global_store_short_d16_hi v[72:73], v81, off offset:128
	v_cvt_pk_bf16_f32 v83, v38, v39
	global_store_short v[72:73], v82, off offset:256
	global_store_short_d16_hi v[72:73], v82, off offset:384
	v_cvt_pk_bf16_f32 v84, v40, v41
	global_store_short v[72:73], v83, off offset:1024
	global_store_short_d16_hi v[72:73], v83, off offset:1152
	v_cvt_pk_bf16_f32 v85, v42, v43
	global_store_short v[72:73], v84, off offset:1280
	global_store_short_d16_hi v[72:73], v84, off offset:1408
	v_cvt_pk_bf16_f32 v86, v44, v45
	global_store_short v[72:73], v85, off offset:2048
	global_store_short_d16_hi v[72:73], v85, off offset:2176
	v_cvt_pk_bf16_f32 v87, v46, v47
	global_store_short v[72:73], v86, off offset:2304
	global_store_short_d16_hi v[72:73], v86, off offset:2432
	v_cvt_pk_bf16_f32 v88, v48, v49
	global_store_short v[72:73], v87, off offset:3072
	global_store_short_d16_hi v[72:73], v87, off offset:3200
	global_store_short v[72:73], v88, off offset:3328
	global_store_short_d16_hi v[72:73], v88, off offset:3456
	s_and_saveexec_b64 s[40:41], s[12:13]
	s_cbranch_execz .LBB0_288
	v_permlane32_swap_b32_e32 v50, v34
	v_permlane32_swap_b32_e32 v51, v35
	v_permlane32_swap_b32_e32 v52, v36
	v_permlane32_swap_b32_e32 v53, v37
	v_ashrrev_i32_e32 v67, 31, v66
	v_permlane32_swap_b32_e32 v54, v38
	v_permlane32_swap_b32_e32 v55, v39
	v_permlane32_swap_b32_e32 v56, v40
	v_permlane32_swap_b32_e32 v57, v41
	v_permlane32_swap_b32_e32 v58, v42
	v_permlane32_swap_b32_e32 v59, v43
	v_permlane32_swap_b32_e32 v60, v44
	v_permlane32_swap_b32_e32 v61, v45
	v_permlane32_swap_b32_e32 v62, v46
	v_permlane32_swap_b32_e32 v63, v47
	v_permlane32_swap_b32_e32 v64, v48
	v_permlane32_swap_b32_e32 v65, v49
	ds_write_b128 v156, v[50:53]
	ds_write_b128 v156, v[34:37] offset:16
	ds_write_b128 v156, v[54:57] offset:32
	ds_write_b128 v156, v[38:41] offset:48
	ds_write_b128 v156, v[58:61] offset:64
	ds_write_b128 v156, v[42:45] offset:80
	ds_write_b128 v156, v[62:65] offset:96
	ds_write_b128 v156, v[46:49] offset:112
	v_lshlrev_b64 v[34:35], 11, v[66:67]
	v_lshl_add_u64 v[34:35], s[26:27], 0, v[34:35]
	v_lshl_add_u64 v[34:35], v[98:99], 2, v[34:35]
	v_lshlrev_b32_e32 v36, 2, v155
	v_mov_b32_e32 v37, v99
	v_lshl_add_u64 v[34:35], v[34:35], 0, v[36:37]
	v_or_b32_e32 v36, v66, v154
	v_cmp_gt_i32_e64 s[14:15], s57, v36
	s_and_saveexec_b64 s[42:43], s[14:15]
	s_cbranch_execz .LBB0_274
	v_lshlrev_b32_e32 v36, 2, v153
	v_mov_b32_e32 v37, v99
	v_lshl_add_u64 v[40:41], v[34:35], 0, v[36:37]
	v_add_u32_e32 v36, v139, v152
	ds_read_b128 v[36:39], v36
	s_waitcnt lgkmcnt(0)
	global_store_dwordx4 v[40:41], v[36:39], off

.LBB0_328:
	s_and_saveexec_b64 s[10:11], s[8:9]
	s_xor_b64 s[14:15], exec, s[10:11]
	s_cbranch_execz .LBB0_380
	v_cmp_gt_i32_e64 s[8:9], s60, v108
	s_and_saveexec_b64 s[10:11], s[30:31]
	s_xor_b64 s[30:31], exec, s[10:11]
	s_cbranch_execz .LBB0_348
	v_ashrrev_i32_e32 v38, 6, v34
	v_ashrrev_i32_e32 v39, 31, v38
	v_lshl_add_u64 v[38:39], v[112:113], 0, v[38:39]
	v_lshlrev_b64 v[38:39], 6, v[38:39]
	v_and_b32_e32 v35, 63, v36
	v_lshlrev_b32_e32 v36, 1, v35
	v_mov_b32_e32 v37, v99
	v_or3_b32 v40, v38, v159, 32
	v_mov_b32_e32 v41, v39
	v_lshl_add_u64 v[36:37], s[24:25], 0, v[36:37]
	v_lshlrev_b64 v[40:41], 7, v[40:41]
	v_cvt_pk_bf16_f32 v35, v2, v3
	v_lshl_add_u64 v[40:41], v[36:37], 0, v[40:41]
	v_cvt_pk_bf16_f32 v42, v4, v5
	global_store_short v[40:41], v35, off offset:-4096
	global_store_short_d16_hi v[40:41], v35, off offset:-3968
	v_cvt_pk_bf16_f32 v43, v6, v7
	global_store_short v[40:41], v42, off offset:-3840
	global_store_short_d16_hi v[40:41], v42, off offset:-3712
	v_cvt_pk_bf16_f32 v44, v8, v9
	global_store_short v[40:41], v43, off offset:-3072
	global_store_short_d16_hi v[40:41], v43, off offset:-2944
	v_cvt_pk_bf16_f32 v45, v10, v11
	global_store_short v[40:41], v44, off offset:-2816
	global_store_short_d16_hi v[40:41], v44, off offset:-2688
	v_cvt_pk_bf16_f32 v46, v12, v13
	global_store_short v[40:41], v45, off offset:-2048
	global_store_short_d16_hi v[40:41], v45, off offset:-1920
	v_cvt_pk_bf16_f32 v47, v14, v15
	global_store_short v[40:41], v46, off offset:-1792
	global_store_short_d16_hi v[40:41], v46, off offset:-1664
	v_cvt_pk_bf16_f32 v48, v16, v17
	global_store_short v[40:41], v47, off offset:-1024
	global_store_short_d16_hi v[40:41], v47, off offset:-896
	v_cvt_pk_bf16_f32 v49, v18, v19
	global_store_short v[40:41], v48, off offset:-768
	global_store_short_d16_hi v[40:41], v48, off offset:-640
	v_cvt_pk_bf16_f32 v50, v20, v21
	global_store_short v[40:41], v49, off
	global_store_short_d16_hi v[40:41], v49, off offset:128
	v_cvt_pk_bf16_f32 v51, v22, v23
	global_store_short v[40:41], v50, off offset:256
	global_store_short_d16_hi v[40:41], v50, off offset:384
	v_cvt_pk_bf16_f32 v52, v24, v25
	global_store_short v[40:41], v51, off offset:1024
	global_store_short_d16_hi v[40:41], v51, off offset:1152
	v_cvt_pk_bf16_f32 v53, v26, v27
	global_store_short v[40:41], v52, off offset:1280
	global_store_short_d16_hi v[40:41], v52, off offset:1408
	v_cvt_pk_bf16_f32 v54, v28, v29
	global_store_short v[40:41], v53, off offset:2048
	global_store_short_d16_hi v[40:41], v53, off offset:2176
	v_cvt_pk_bf16_f32 v55, v30, v31
	global_store_short v[40:41], v54, off offset:2304
	global_store_short_d16_hi v[40:41], v54, off offset:2432
	v_cvt_pk_bf16_f32 v56, v32, v33
	global_store_short v[40:41], v55, off offset:3072
	global_store_short_d16_hi v[40:41], v55, off offset:3200
	global_store_short v[40:41], v56, off offset:3328
	global_store_short_d16_hi v[40:41], v56, off offset:3456
	s_and_saveexec_b64 s[34:35], s[8:9]
	s_cbranch_execz .LBB0_347
	v_permlane32_swap_b32_e32 v2, v18
	v_permlane32_swap_b32_e32 v3, v19
	v_permlane32_swap_b32_e32 v4, v20
	v_permlane32_swap_b32_e32 v5, v21
	v_ashrrev_i32_e32 v35, 31, v34
	v_permlane32_swap_b32_e32 v6, v22
	v_permlane32_swap_b32_e32 v7, v23
	v_permlane32_swap_b32_e32 v8, v24
	v_permlane32_swap_b32_e32 v9, v25
	v_permlane32_swap_b32_e32 v10, v26
	v_permlane32_swap_b32_e32 v11, v27
	v_permlane32_swap_b32_e32 v12, v28
	v_permlane32_swap_b32_e32 v13, v29
	v_permlane32_swap_b32_e32 v14, v30
	v_permlane32_swap_b32_e32 v15, v31
	v_permlane32_swap_b32_e32 v16, v32
	v_permlane32_swap_b32_e32 v17, v33
	ds_write_b128 v156, v[2:5]
	ds_write_b128 v156, v[18:21] offset:16
	ds_write_b128 v156, v[6:9] offset:32
	ds_write_b128 v156, v[22:25] offset:48
	ds_write_b128 v156, v[10:13] offset:64
	ds_write_b128 v156, v[26:29] offset:80
	ds_write_b128 v156, v[14:17] offset:96
	ds_write_b128 v156, v[30:33] offset:112
	v_lshlrev_b64 v[2:3], 11, v[34:35]
	v_lshl_add_u64 v[2:3], s[26:27], 0, v[2:3]
	v_lshl_add_u64 v[2:3], v[98:99], 2, v[2:3]
	v_lshlrev_b32_e32 v98, 2, v155
	v_or_b32_e32 v4, v34, v154
	v_lshl_add_u64 v[2:3], v[2:3], 0, v[98:99]
	v_cmp_gt_i32_e64 s[10:11], s57, v4
	s_and_saveexec_b64 s[36:37], s[10:11]
	s_cbranch_execz .LBB0_333
	v_add_u32_e32 v4, v139, v152
	ds_read_b128 v[4:7], v4
	v_lshlrev_b32_e32 v98, 2, v153
	v_lshl_add_u64 v[8:9], v[2:3], 0, v[98:99]
	s_waitcnt lgkmcnt(0)
	global_store_dwordx4 v[8:9], v[4:7], off
